# scan pass 1 item prologue: up-projection matrix staging and per-channel parameter loads issued together with one wait each (were 4 + 7 serial round trips)
# baseline (speedup 1.0000x reference)
; #define LAS __attribute__((address_space(3)))
; __device__ __forceinline__ unsigned pk2(float lo, float hi) { f32x2 v = {lo, hi}; bf16x2_t b = __builtin_convertvector(v, bf16x2_t); return __builtin_bit_cast(unsigned, b); }
; __device__ __forceinline__ void scan_pass1(const ScanP& sp, int b, int h, int seg, LAS unsigned char* lds) {
;     ...
;     for (int e = tid; e < 2048; e += 512) { const int m = e >> 6, j = e & 63;
;         ((LAS unsigned short*)(lds + O_WUP))[j * 40 + m] = (unsigned short)(pk2(sp.w_up[m * 512 + h * 64 + j], 0.f) & 0xffffu);
;         ((LAS unsigned short*)(lds + O_WUP + 5120))[j * 40 + m] = (unsigned short)(pk2(sp.a_up[m * 512 + h * 64 + j], 0.f) & 0xffffu); }
;     LAS float* par = (LAS float*)(lds + 98048);
;     if (tid < 64) {
;         const int c_ = h * 64 + tid;
;         par[0 * 64 + tid] = sp.mu[c_]; par[1 * 64 + tid] = sp.mu[512 + c_]; par[2 * 64 + tid] = sp.mu[1024 + c_]; par[3 * 64 + tid] = sp.mu[1536 + tid];
;         par[4 * 64 + tid] = sp.w0[c_]; par[5 * 64 + tid] = sp.a0[c_]; par[6 * 64 + tid] = sp.kkr[c_]; par[7 * 64 + tid] = sp.kkr[512 + c_]; par[8 * 64 + tid] = sp.kkr[1024 + c_];
;         par[9 * 64 + tid] = sp.ln_gain[c_] * sp.out_gain[1536 + c_]; par[10 * 64 + tid] = sp.ln_bias[c_];
;     }
.LBB0_246:
	v_ashrrev_i32_e32 v8, 6, v3
	v_lshl_or_b32 v4, v8, 9, v2
	v_lshlrev_b32_e32 v4, 2, v4
	v_add_u32_e32 v5, 0x4000, v4
	v_add_u32_e32 v6, 0x8000, v4
	v_add_u32_e32 v9, 0xc000, v4
	global_load_dword v230, v4, s[66:67]
	global_load_dword v234, v4, s[86:87]
	global_load_dword v231, v5, s[66:67]
	global_load_dword v235, v5, s[86:87]
	global_load_dword v232, v6, s[66:67]
	global_load_dword v236, v6, s[86:87]
	global_load_dword v233, v9, s[66:67]
	global_load_dword v237, v9, s[86:87]
	v_add_u32_e32 v7, v8, v0
	v_lshl_add_u32 v7, v7, 1, 0
	v_add_u32_e32 v3, 0x800, v3
	s_waitcnt vmcnt(0)
	v_cvt_pk_bf16_f32 v230, v230, s0
	v_cvt_pk_bf16_f32 v234, v234, s0
	ds_write_b16 v7, v230 offset:5120
	ds_write_b16 v7, v234
	v_cvt_pk_bf16_f32 v231, v231, s0
	v_cvt_pk_bf16_f32 v235, v235, s0
	ds_write_b16 v7, v231 offset:5136
	ds_write_b16 v7, v235 offset:16
	v_cvt_pk_bf16_f32 v232, v232, s0
	v_cvt_pk_bf16_f32 v236, v236, s0
	ds_write_b16 v7, v232 offset:5152
	ds_write_b16 v7, v236 offset:32
	v_cvt_pk_bf16_f32 v233, v233, s0
	v_cvt_pk_bf16_f32 v237, v237, s0
	ds_write_b16 v7, v233 offset:5168
	ds_write_b16 v7, v237 offset:48
.LBB0_247:
	s_or_b64 exec, exec, s[0:1]
	v_cmp_gt_i32_e32 vcc, 64, v36
	s_and_saveexec_b64 s[0:1], vcc
	s_cbranch_execz .LBB0_249
	s_waitcnt vmcnt(0)
	v_add_u32_e32 v2, s4, v36
	v_ashrrev_i32_e32 v3, 31, v2
	v_lshlrev_b64 v[2:3], 2, v[2:3]
	v_ashrrev_i32_e32 v37, 31, v36
	v_lshl_add_u32 v6, v36, 2, 0
	v_add_u32_e32 v6, 0x17f00, v6
	v_readlane_b32 s2, v254, 42
	v_readlane_b32 s3, v254, 43
	s_nop 1
	v_lshl_add_u64 v[4:5], s[2:3], 0, v[2:3]
	global_load_dword v230, v[4:5], off
	global_load_dword v231, v[4:5], off offset:2048
	v_add_co_u32_e32 v4, vcc, 0x1000, v4
	s_nop 1
	v_addc_co_u32_e32 v5, vcc, 0, v5, vcc
	global_load_dword v232, v[4:5], off
	v_lshl_add_u64 v[242:243], v[36:37], 2, s[2:3]
	v_add_co_u32_e32 v242, vcc, 0x1000, v242
	s_nop 1
	v_addc_co_u32_e32 v243, vcc, 0, v243, vcc
	global_load_dword v233, v[242:243], off offset:2048
	v_readlane_b32 s2, v254, 44
	v_readlane_b32 s3, v254, 45
	s_nop 1
	v_lshl_add_u64 v[4:5], s[2:3], 0, v[2:3]
	global_load_dword v234, v[4:5], off
	v_readlane_b32 s2, v254, 46
	v_readlane_b32 s3, v254, 47
	s_nop 1
	v_lshl_add_u64 v[4:5], s[2:3], 0, v[2:3]
	global_load_dword v235, v[4:5], off
	v_readlane_b32 s2, v254, 48
	v_readlane_b32 s3, v254, 49
	s_nop 1
	v_lshl_add_u64 v[4:5], s[2:3], 0, v[2:3]
	global_load_dword v236, v[4:5], off
	global_load_dword v237, v[4:5], off offset:2048
	v_add_co_u32_e32 v4, vcc, s21, v4
	s_nop 1
	v_addc_co_u32_e32 v5, vcc, 0, v5, vcc
	global_load_dword v238, v[4:5], off
	v_readlane_b32 s2, v254, 50
	v_readlane_b32 s3, v254, 51
	s_nop 1
	v_lshl_add_u64 v[4:5], s[2:3], 0, v[2:3]
	global_load_dword v239, v[4:5], off
	v_readlane_b32 s2, v254, 54
	v_readlane_b32 s3, v254, 55
	s_nop 1
	v_lshl_add_u64 v[4:5], s[2:3], 0, v[2:3]
	v_add_co_u32_e32 v4, vcc, 0x1000, v4
	s_nop 1
	v_addc_co_u32_e32 v5, vcc, 0, v5, vcc
	global_load_dword v240, v[4:5], off offset:2048
	v_readlane_b32 s2, v254, 52
	v_readlane_b32 s3, v254, 53
	s_nop 1
	v_lshl_add_u64 v[4:5], s[2:3], 0, v[2:3]
	global_load_dword v241, v[4:5], off
	s_waitcnt vmcnt(0)
	ds_write2st64_b32 v6, v230, v231 offset1:1
	ds_write2st64_b32 v6, v232, v233 offset0:2 offset1:3
	ds_write2st64_b32 v6, v234, v235 offset0:4 offset1:5
	ds_write2st64_b32 v6, v236, v237 offset0:6 offset1:7
	v_mul_f32_e32 v239, v239, v240
	ds_write2st64_b32 v6, v238, v239 offset0:8 offset1:9
	ds_write_b32 v6, v241 offset:2560
